# GATEACC epilogue: nontemporal loads for the gate operand
# speedup vs baseline: 1.0080x; 1.0080x over previous
.LBB0_752:
	s_cmp_eq_u32 s58, 4
	s_mov_b64 s[8:9], -1
	s_cbranch_scc0 .LBB0_786
	s_lshl_b32 s8, s88, 8
	s_ashr_i32 s27, s88, 2
	s_and_b32 s8, s8, 0x300
	v_add_u32_e32 v130, s8, v184
	s_lshl_b32 s34, s27, 10
	v_mov_b64_e32 v[132:133], s[24:25]
	v_ashrrev_i32_e32 v131, 31, v130
	s_ashr_i32 s35, s34, 31
	v_mad_i64_i32 v[132:133], s[8:9], v186, s67, v[132:133]
	v_lshlrev_b64 v[130:131], 1, v[130:131]
	v_lshl_add_u64 v[132:133], s[34:35], 1, v[132:133]
	v_lshl_add_u64 v[156:157], v[132:133], 0, v[130:131]
	v_ashrrev_i32_e32 v136, 31, v186
	v_mul_lo_u32 v137, s13, v186
	v_mad_u64_u32 v[132:133], s[8:9], s12, v186, 0
	v_mul_lo_u32 v134, s12, v136
	v_add3_u32 v133, v133, v134, v137
	v_lshl_add_u64 v[132:133], v[132:133], 1, s[22:23]
	v_lshl_add_u64 v[160:161], v[132:133], 0, v[130:131]
	v_mov_b32_e32 v158, v160
	v_mov_b32_e32 v159, v161
	s_mov_b32 s34, 0x18000
	s_mov_b32 s35, 0
	s_mov_b32 s8, 0x78000
	s_mov_b32 s9, 0
	s_lshl_b32 s36, s12, 5
	s_mov_b32 s37, 0
	s_mul_i32 vcc_lo, s12, 0xa0
	s_mov_b32 vcc_hi, 0
	s_cmp_lt_i32 s27, 1
	s_cbranch_scc1 .Lga_first
	global_load_dwordx4 v[186:189], v[156:157], off nt
	global_load_dwordx4 v[190:193], v[158:159], off
	global_load_dwordx4 v[194:197], v[156:157], off offset:256 nt
	global_load_dwordx4 v[198:201], v[158:159], off offset:256
	v_lshl_add_u64 v[156:157], v[156:157], 0, s[34:35]
	v_lshl_add_u64 v[158:159], v[158:159], 0, s[36:37]
	global_load_dwordx4 v[202:205], v[156:157], off nt
	global_load_dwordx4 v[206:209], v[158:159], off
	global_load_dwordx4 v[210:213], v[156:157], off offset:256 nt
	global_load_dwordx4 v[214:217], v[158:159], off offset:256
	v_lshl_add_u64 v[156:157], v[156:157], 0, s[34:35]
	v_lshl_add_u64 v[158:159], v[158:159], 0, s[36:37]
	global_load_dwordx4 v[218:221], v[156:157], off nt
	global_load_dwordx4 v[222:225], v[158:159], off
	global_load_dwordx4 v[226:229], v[156:157], off offset:256 nt
	global_load_dwordx4 v[230:233], v[158:159], off offset:256
	v_lshl_add_u64 v[156:157], v[156:157], 0, s[34:35]
	v_lshl_add_u64 v[158:159], v[158:159], 0, s[36:37]
	global_load_dwordx4 v[234:237], v[156:157], off nt
	global_load_dwordx4 v[238:241], v[158:159], off
	global_load_dwordx4 v[242:245], v[156:157], off offset:256 nt
	global_load_dwordx4 v[246:249], v[158:159], off offset:256
	v_lshl_add_u64 v[156:157], v[156:157], 0, s[8:9]
	v_lshl_add_u64 v[158:159], v[158:159], 0, vcc
	s_waitcnt vmcnt(14)
	v_lshlrev_b32_e32 v130, 16, v186
	v_mul_f32_e32 v126, v126, v130
	v_and_b32_e32 v131, 0xffff0000, v186
	v_mul_f32_e32 v127, v127, v131
	v_lshlrev_b32_e32 v130, 16, v187
	v_mul_f32_e32 v128, v128, v130
	v_and_b32_e32 v131, 0xffff0000, v187
	v_mul_f32_e32 v129, v129, v131
	v_lshlrev_b32_e32 v130, 16, v188
	v_mul_f32_e32 v122, v122, v130
	v_and_b32_e32 v131, 0xffff0000, v188
	v_mul_f32_e32 v123, v123, v131
	v_lshlrev_b32_e32 v130, 16, v189
	v_mul_f32_e32 v124, v124, v130
	v_and_b32_e32 v131, 0xffff0000, v189
	v_mul_f32_e32 v125, v125, v131
	v_lshlrev_b32_e32 v130, 16, v190
	v_add_f32_e32 v126, v126, v130
	v_and_b32_e32 v131, 0xffff0000, v190
	v_add_f32_e32 v127, v127, v131
	v_lshlrev_b32_e32 v130, 16, v191
	v_add_f32_e32 v128, v128, v130
	v_and_b32_e32 v131, 0xffff0000, v191
	v_add_f32_e32 v129, v129, v131
	v_lshlrev_b32_e32 v130, 16, v192
	v_add_f32_e32 v122, v122, v130
	v_and_b32_e32 v131, 0xffff0000, v192
	v_add_f32_e32 v123, v123, v131
	v_lshlrev_b32_e32 v130, 16, v193
	v_add_f32_e32 v124, v124, v130
	v_and_b32_e32 v131, 0xffff0000, v193
	v_add_f32_e32 v125, v125, v131
	v_cvt_pk_bf16_f32 v126, v126, v127
	v_cvt_pk_bf16_f32 v127, v128, v129
	v_cvt_pk_bf16_f32 v128, v122, v123
	v_cvt_pk_bf16_f32 v129, v124, v125
	s_waitcnt vmcnt(12)
	v_lshlrev_b32_e32 v130, 16, v194
	v_mul_f32_e32 v118, v118, v130
	v_and_b32_e32 v131, 0xffff0000, v194
	v_mul_f32_e32 v119, v119, v131
	v_lshlrev_b32_e32 v130, 16, v195
	v_mul_f32_e32 v120, v120, v130
	v_and_b32_e32 v131, 0xffff0000, v195
	v_mul_f32_e32 v121, v121, v131
	v_lshlrev_b32_e32 v130, 16, v196
	v_mul_f32_e32 v114, v114, v130
	v_and_b32_e32 v131, 0xffff0000, v196
	v_mul_f32_e32 v115, v115, v131
	v_lshlrev_b32_e32 v130, 16, v197
	v_mul_f32_e32 v116, v116, v130
	v_and_b32_e32 v131, 0xffff0000, v197
	v_mul_f32_e32 v117, v117, v131
	v_lshlrev_b32_e32 v130, 16, v198
	v_add_f32_e32 v118, v118, v130
	v_and_b32_e32 v131, 0xffff0000, v198
	v_add_f32_e32 v119, v119, v131
	v_lshlrev_b32_e32 v130, 16, v199
	v_add_f32_e32 v120, v120, v130
	v_and_b32_e32 v131, 0xffff0000, v199
	v_add_f32_e32 v121, v121, v131
	v_lshlrev_b32_e32 v130, 16, v200
	v_add_f32_e32 v114, v114, v130
	v_and_b32_e32 v131, 0xffff0000, v200
	v_add_f32_e32 v115, v115, v131
	v_lshlrev_b32_e32 v130, 16, v201
	v_add_f32_e32 v116, v116, v130
	v_and_b32_e32 v131, 0xffff0000, v201
	v_add_f32_e32 v117, v117, v131
	v_cvt_pk_bf16_f32 v118, v118, v119
	v_cvt_pk_bf16_f32 v119, v120, v121
	v_cvt_pk_bf16_f32 v120, v114, v115
	v_cvt_pk_bf16_f32 v121, v116, v117
	s_waitcnt vmcnt(10)
	v_lshlrev_b32_e32 v130, 16, v202
	v_mul_f32_e32 v110, v110, v130
	v_and_b32_e32 v131, 0xffff0000, v202
	v_mul_f32_e32 v111, v111, v131
	v_lshlrev_b32_e32 v130, 16, v203
	v_mul_f32_e32 v112, v112, v130
	v_and_b32_e32 v131, 0xffff0000, v203
	v_mul_f32_e32 v113, v113, v131
	v_lshlrev_b32_e32 v130, 16, v204
	v_mul_f32_e32 v106, v106, v130
	v_and_b32_e32 v131, 0xffff0000, v204
	v_mul_f32_e32 v107, v107, v131
	v_lshlrev_b32_e32 v130, 16, v205
	v_mul_f32_e32 v108, v108, v130
	v_and_b32_e32 v131, 0xffff0000, v205
	v_mul_f32_e32 v109, v109, v131
	v_lshlrev_b32_e32 v130, 16, v206
	v_add_f32_e32 v110, v110, v130
	v_and_b32_e32 v131, 0xffff0000, v206
	v_add_f32_e32 v111, v111, v131
	v_lshlrev_b32_e32 v130, 16, v207
	v_add_f32_e32 v112, v112, v130
	v_and_b32_e32 v131, 0xffff0000, v207
	v_add_f32_e32 v113, v113, v131
	v_lshlrev_b32_e32 v130, 16, v208
	v_add_f32_e32 v106, v106, v130
	v_and_b32_e32 v131, 0xffff0000, v208
	v_add_f32_e32 v107, v107, v131
	v_lshlrev_b32_e32 v130, 16, v209
	v_add_f32_e32 v108, v108, v130
	v_and_b32_e32 v131, 0xffff0000, v209
	v_add_f32_e32 v109, v109, v131
	v_cvt_pk_bf16_f32 v110, v110, v111
	v_cvt_pk_bf16_f32 v111, v112, v113
	v_cvt_pk_bf16_f32 v112, v106, v107
	v_cvt_pk_bf16_f32 v113, v108, v109
	s_waitcnt vmcnt(8)
	v_lshlrev_b32_e32 v130, 16, v210
	v_mul_f32_e32 v102, v102, v130
	v_and_b32_e32 v131, 0xffff0000, v210
	v_mul_f32_e32 v103, v103, v131
	v_lshlrev_b32_e32 v130, 16, v211
	v_mul_f32_e32 v104, v104, v130
	v_and_b32_e32 v131, 0xffff0000, v211
	v_mul_f32_e32 v105, v105, v131
	v_lshlrev_b32_e32 v130, 16, v212
	v_mul_f32_e32 v98, v98, v130
	v_and_b32_e32 v131, 0xffff0000, v212
	v_mul_f32_e32 v99, v99, v131
	v_lshlrev_b32_e32 v130, 16, v213
	v_mul_f32_e32 v100, v100, v130
	v_and_b32_e32 v131, 0xffff0000, v213
	v_mul_f32_e32 v101, v101, v131
	v_lshlrev_b32_e32 v130, 16, v214
	v_add_f32_e32 v102, v102, v130
	v_and_b32_e32 v131, 0xffff0000, v214
	v_add_f32_e32 v103, v103, v131
	v_lshlrev_b32_e32 v130, 16, v215
	v_add_f32_e32 v104, v104, v130
	v_and_b32_e32 v131, 0xffff0000, v215
	v_add_f32_e32 v105, v105, v131
	v_lshlrev_b32_e32 v130, 16, v216
	v_add_f32_e32 v98, v98, v130
	v_and_b32_e32 v131, 0xffff0000, v216
	v_add_f32_e32 v99, v99, v131
	v_lshlrev_b32_e32 v130, 16, v217
	v_add_f32_e32 v100, v100, v130
	v_and_b32_e32 v131, 0xffff0000, v217
	v_add_f32_e32 v101, v101, v131
	v_cvt_pk_bf16_f32 v102, v102, v103
	v_cvt_pk_bf16_f32 v103, v104, v105
	v_cvt_pk_bf16_f32 v104, v98, v99
	v_cvt_pk_bf16_f32 v105, v100, v101
	global_load_dwordx4 v[186:189], v[156:157], off nt
	global_load_dwordx4 v[190:193], v[158:159], off
	global_load_dwordx4 v[194:197], v[156:157], off offset:256 nt
	global_load_dwordx4 v[198:201], v[158:159], off offset:256
	v_lshl_add_u64 v[156:157], v[156:157], 0, s[34:35]
	v_lshl_add_u64 v[158:159], v[158:159], 0, s[36:37]
	global_load_dwordx4 v[202:205], v[156:157], off nt
	global_load_dwordx4 v[206:209], v[158:159], off
	global_load_dwordx4 v[210:213], v[156:157], off offset:256 nt
	global_load_dwordx4 v[214:217], v[158:159], off offset:256
	v_lshl_add_u64 v[156:157], v[156:157], 0, s[34:35]
	v_lshl_add_u64 v[158:159], v[158:159], 0, s[36:37]
	s_waitcnt vmcnt(14)
	v_lshlrev_b32_e32 v130, 16, v218
	v_mul_f32_e32 v94, v94, v130
	v_and_b32_e32 v131, 0xffff0000, v218
	v_mul_f32_e32 v95, v95, v131
	v_lshlrev_b32_e32 v130, 16, v219
	v_mul_f32_e32 v96, v96, v130
	v_and_b32_e32 v131, 0xffff0000, v219
	v_mul_f32_e32 v97, v97, v131
	v_lshlrev_b32_e32 v130, 16, v220
	v_mul_f32_e32 v90, v90, v130
	v_and_b32_e32 v131, 0xffff0000, v220
	v_mul_f32_e32 v91, v91, v131
	v_lshlrev_b32_e32 v130, 16, v221
	v_mul_f32_e32 v92, v92, v130
	v_and_b32_e32 v131, 0xffff0000, v221
	v_mul_f32_e32 v93, v93, v131
	v_lshlrev_b32_e32 v130, 16, v222
	v_add_f32_e32 v94, v94, v130
	v_and_b32_e32 v131, 0xffff0000, v222
	v_add_f32_e32 v95, v95, v131
	v_lshlrev_b32_e32 v130, 16, v223
	v_add_f32_e32 v96, v96, v130
	v_and_b32_e32 v131, 0xffff0000, v223
	v_add_f32_e32 v97, v97, v131
	v_lshlrev_b32_e32 v130, 16, v224
	v_add_f32_e32 v90, v90, v130
	v_and_b32_e32 v131, 0xffff0000, v224
	v_add_f32_e32 v91, v91, v131
	v_lshlrev_b32_e32 v130, 16, v225
	v_add_f32_e32 v92, v92, v130
	v_and_b32_e32 v131, 0xffff0000, v225
	v_add_f32_e32 v93, v93, v131
	v_cvt_pk_bf16_f32 v94, v94, v95
	v_cvt_pk_bf16_f32 v95, v96, v97
	v_cvt_pk_bf16_f32 v96, v90, v91
	v_cvt_pk_bf16_f32 v97, v92, v93
	s_waitcnt vmcnt(12)
	v_lshlrev_b32_e32 v130, 16, v226
	v_mul_f32_e32 v86, v86, v130
	v_and_b32_e32 v131, 0xffff0000, v226
	v_mul_f32_e32 v87, v87, v131
	v_lshlrev_b32_e32 v130, 16, v227
	v_mul_f32_e32 v88, v88, v130
	v_and_b32_e32 v131, 0xffff0000, v227
	v_mul_f32_e32 v89, v89, v131
	v_lshlrev_b32_e32 v130, 16, v228
	v_mul_f32_e32 v82, v82, v130
	v_and_b32_e32 v131, 0xffff0000, v228
	v_mul_f32_e32 v83, v83, v131
	v_lshlrev_b32_e32 v130, 16, v229
	v_mul_f32_e32 v84, v84, v130
	v_and_b32_e32 v131, 0xffff0000, v229
	v_mul_f32_e32 v85, v85, v131
	v_lshlrev_b32_e32 v130, 16, v230
	v_add_f32_e32 v86, v86, v130
	v_and_b32_e32 v131, 0xffff0000, v230
	v_add_f32_e32 v87, v87, v131
	v_lshlrev_b32_e32 v130, 16, v231
	v_add_f32_e32 v88, v88, v130
	v_and_b32_e32 v131, 0xffff0000, v231
	v_add_f32_e32 v89, v89, v131
	v_lshlrev_b32_e32 v130, 16, v232
	v_add_f32_e32 v82, v82, v130
	v_and_b32_e32 v131, 0xffff0000, v232
	v_add_f32_e32 v83, v83, v131
	v_lshlrev_b32_e32 v130, 16, v233
	v_add_f32_e32 v84, v84, v130
	v_and_b32_e32 v131, 0xffff0000, v233
	v_add_f32_e32 v85, v85, v131
	v_cvt_pk_bf16_f32 v86, v86, v87
	v_cvt_pk_bf16_f32 v87, v88, v89
	v_cvt_pk_bf16_f32 v88, v82, v83
	v_cvt_pk_bf16_f32 v89, v84, v85
	s_waitcnt vmcnt(10)
	v_lshlrev_b32_e32 v130, 16, v234
	v_mul_f32_e32 v78, v78, v130
	v_and_b32_e32 v131, 0xffff0000, v234
	v_mul_f32_e32 v79, v79, v131
	v_lshlrev_b32_e32 v130, 16, v235
	v_mul_f32_e32 v80, v80, v130
	v_and_b32_e32 v131, 0xffff0000, v235
	v_mul_f32_e32 v81, v81, v131
	v_lshlrev_b32_e32 v130, 16, v236
	v_mul_f32_e32 v74, v74, v130
	v_and_b32_e32 v131, 0xffff0000, v236
	v_mul_f32_e32 v75, v75, v131
	v_lshlrev_b32_e32 v130, 16, v237
	v_mul_f32_e32 v76, v76, v130
	v_and_b32_e32 v131, 0xffff0000, v237
	v_mul_f32_e32 v77, v77, v131
	v_lshlrev_b32_e32 v130, 16, v238
	v_add_f32_e32 v78, v78, v130
	v_and_b32_e32 v131, 0xffff0000, v238
	v_add_f32_e32 v79, v79, v131
	v_lshlrev_b32_e32 v130, 16, v239
	v_add_f32_e32 v80, v80, v130
	v_and_b32_e32 v131, 0xffff0000, v239
	v_add_f32_e32 v81, v81, v131
	v_lshlrev_b32_e32 v130, 16, v240
	v_add_f32_e32 v74, v74, v130
	v_and_b32_e32 v131, 0xffff0000, v240
	v_add_f32_e32 v75, v75, v131
	v_lshlrev_b32_e32 v130, 16, v241
	v_add_f32_e32 v76, v76, v130
	v_and_b32_e32 v131, 0xffff0000, v241
	v_add_f32_e32 v77, v77, v131
	v_cvt_pk_bf16_f32 v78, v78, v79
	v_cvt_pk_bf16_f32 v79, v80, v81
	v_cvt_pk_bf16_f32 v80, v74, v75
	v_cvt_pk_bf16_f32 v81, v76, v77
	s_waitcnt vmcnt(8)
	v_lshlrev_b32_e32 v130, 16, v242
	v_mul_f32_e32 v70, v70, v130
	v_and_b32_e32 v131, 0xffff0000, v242
	v_mul_f32_e32 v71, v71, v131
	v_lshlrev_b32_e32 v130, 16, v243
	v_mul_f32_e32 v72, v72, v130
	v_and_b32_e32 v131, 0xffff0000, v243
	v_mul_f32_e32 v73, v73, v131
	v_lshlrev_b32_e32 v130, 16, v244
	v_mul_f32_e32 v66, v66, v130
	v_and_b32_e32 v131, 0xffff0000, v244
	v_mul_f32_e32 v67, v67, v131
	v_lshlrev_b32_e32 v130, 16, v245
	v_mul_f32_e32 v68, v68, v130
	v_and_b32_e32 v131, 0xffff0000, v245
	v_mul_f32_e32 v69, v69, v131
	v_lshlrev_b32_e32 v130, 16, v246
	v_add_f32_e32 v70, v70, v130
	v_and_b32_e32 v131, 0xffff0000, v246
	v_add_f32_e32 v71, v71, v131
	v_lshlrev_b32_e32 v130, 16, v247
	v_add_f32_e32 v72, v72, v130
	v_and_b32_e32 v131, 0xffff0000, v247
	v_add_f32_e32 v73, v73, v131
	v_lshlrev_b32_e32 v130, 16, v248
	v_add_f32_e32 v66, v66, v130
	v_and_b32_e32 v131, 0xffff0000, v248
	v_add_f32_e32 v67, v67, v131
	v_lshlrev_b32_e32 v130, 16, v249
	v_add_f32_e32 v68, v68, v130
	v_and_b32_e32 v131, 0xffff0000, v249
	v_add_f32_e32 v69, v69, v131
	v_cvt_pk_bf16_f32 v70, v70, v71
	v_cvt_pk_bf16_f32 v71, v72, v73
	v_cvt_pk_bf16_f32 v72, v66, v67
	v_cvt_pk_bf16_f32 v73, v68, v69
	global_load_dwordx4 v[218:221], v[156:157], off nt
	global_load_dwordx4 v[222:225], v[158:159], off
	global_load_dwordx4 v[226:229], v[156:157], off offset:256 nt
	global_load_dwordx4 v[230:233], v[158:159], off offset:256
	v_lshl_add_u64 v[156:157], v[156:157], 0, s[34:35]
	v_lshl_add_u64 v[158:159], v[158:159], 0, s[36:37]
	global_load_dwordx4 v[234:237], v[156:157], off nt
	global_load_dwordx4 v[238:241], v[158:159], off
	global_load_dwordx4 v[242:245], v[156:157], off offset:256 nt
	global_load_dwordx4 v[246:249], v[158:159], off offset:256
	s_waitcnt vmcnt(14)
	v_lshlrev_b32_e32 v130, 16, v186
	v_mul_f32_e32 v62, v62, v130
	v_and_b32_e32 v131, 0xffff0000, v186
	v_mul_f32_e32 v63, v63, v131
	v_lshlrev_b32_e32 v130, 16, v187
	v_mul_f32_e32 v64, v64, v130
	v_and_b32_e32 v131, 0xffff0000, v187
	v_mul_f32_e32 v65, v65, v131
	v_lshlrev_b32_e32 v130, 16, v188
	v_mul_f32_e32 v58, v58, v130
	v_and_b32_e32 v131, 0xffff0000, v188
	v_mul_f32_e32 v59, v59, v131
	v_lshlrev_b32_e32 v130, 16, v189
	v_mul_f32_e32 v60, v60, v130
	v_and_b32_e32 v131, 0xffff0000, v189
	v_mul_f32_e32 v61, v61, v131
	v_lshlrev_b32_e32 v130, 16, v190
	v_add_f32_e32 v62, v62, v130
	v_and_b32_e32 v131, 0xffff0000, v190
	v_add_f32_e32 v63, v63, v131
	v_lshlrev_b32_e32 v130, 16, v191
	v_add_f32_e32 v64, v64, v130
	v_and_b32_e32 v131, 0xffff0000, v191
	v_add_f32_e32 v65, v65, v131
	v_lshlrev_b32_e32 v130, 16, v192
	v_add_f32_e32 v58, v58, v130
	v_and_b32_e32 v131, 0xffff0000, v192
	v_add_f32_e32 v59, v59, v131
	v_lshlrev_b32_e32 v130, 16, v193
	v_add_f32_e32 v60, v60, v130
	v_and_b32_e32 v131, 0xffff0000, v193
	v_add_f32_e32 v61, v61, v131
	v_cvt_pk_bf16_f32 v62, v62, v63
	v_cvt_pk_bf16_f32 v63, v64, v65
	v_cvt_pk_bf16_f32 v64, v58, v59
	v_cvt_pk_bf16_f32 v65, v60, v61
	s_waitcnt vmcnt(12)
	v_lshlrev_b32_e32 v130, 16, v194
	v_mul_f32_e32 v54, v54, v130
	v_and_b32_e32 v131, 0xffff0000, v194
	v_mul_f32_e32 v55, v55, v131
	v_lshlrev_b32_e32 v130, 16, v195
	v_mul_f32_e32 v56, v56, v130
	v_and_b32_e32 v131, 0xffff0000, v195
	v_mul_f32_e32 v57, v57, v131
	v_lshlrev_b32_e32 v130, 16, v196
	v_mul_f32_e32 v50, v50, v130
	v_and_b32_e32 v131, 0xffff0000, v196
	v_mul_f32_e32 v51, v51, v131
	v_lshlrev_b32_e32 v130, 16, v197
	v_mul_f32_e32 v52, v52, v130
	v_and_b32_e32 v131, 0xffff0000, v197
	v_mul_f32_e32 v53, v53, v131
	v_lshlrev_b32_e32 v130, 16, v198
	v_add_f32_e32 v54, v54, v130
	v_and_b32_e32 v131, 0xffff0000, v198
	v_add_f32_e32 v55, v55, v131
	v_lshlrev_b32_e32 v130, 16, v199
	v_add_f32_e32 v56, v56, v130
	v_and_b32_e32 v131, 0xffff0000, v199
	v_add_f32_e32 v57, v57, v131
	v_lshlrev_b32_e32 v130, 16, v200
	v_add_f32_e32 v50, v50, v130
	v_and_b32_e32 v131, 0xffff0000, v200
	v_add_f32_e32 v51, v51, v131
	v_lshlrev_b32_e32 v130, 16, v201
	v_add_f32_e32 v52, v52, v130
	v_and_b32_e32 v131, 0xffff0000, v201
	v_add_f32_e32 v53, v53, v131
	v_cvt_pk_bf16_f32 v54, v54, v55
	v_cvt_pk_bf16_f32 v55, v56, v57
	v_cvt_pk_bf16_f32 v56, v50, v51
	v_cvt_pk_bf16_f32 v57, v52, v53
	s_waitcnt vmcnt(10)
	v_lshlrev_b32_e32 v130, 16, v202
	v_mul_f32_e32 v46, v46, v130
	v_and_b32_e32 v131, 0xffff0000, v202
	v_mul_f32_e32 v47, v47, v131
	v_lshlrev_b32_e32 v130, 16, v203
	v_mul_f32_e32 v48, v48, v130
	v_and_b32_e32 v131, 0xffff0000, v203
	v_mul_f32_e32 v49, v49, v131
	v_lshlrev_b32_e32 v130, 16, v204
	v_mul_f32_e32 v42, v42, v130
	v_and_b32_e32 v131, 0xffff0000, v204
	v_mul_f32_e32 v43, v43, v131
	v_lshlrev_b32_e32 v130, 16, v205
	v_mul_f32_e32 v44, v44, v130
	v_and_b32_e32 v131, 0xffff0000, v205
	v_mul_f32_e32 v45, v45, v131
	v_lshlrev_b32_e32 v130, 16, v206
	v_add_f32_e32 v46, v46, v130
	v_and_b32_e32 v131, 0xffff0000, v206
	v_add_f32_e32 v47, v47, v131
	v_lshlrev_b32_e32 v130, 16, v207
	v_add_f32_e32 v48, v48, v130
	v_and_b32_e32 v131, 0xffff0000, v207
	v_add_f32_e32 v49, v49, v131
	v_lshlrev_b32_e32 v130, 16, v208
	v_add_f32_e32 v42, v42, v130
	v_and_b32_e32 v131, 0xffff0000, v208
	v_add_f32_e32 v43, v43, v131
	v_lshlrev_b32_e32 v130, 16, v209
	v_add_f32_e32 v44, v44, v130
	v_and_b32_e32 v131, 0xffff0000, v209
	v_add_f32_e32 v45, v45, v131
	v_cvt_pk_bf16_f32 v46, v46, v47
	v_cvt_pk_bf16_f32 v47, v48, v49
	v_cvt_pk_bf16_f32 v48, v42, v43
	v_cvt_pk_bf16_f32 v49, v44, v45
	s_waitcnt vmcnt(8)
	v_lshlrev_b32_e32 v130, 16, v210
	v_mul_f32_e32 v38, v38, v130
	v_and_b32_e32 v131, 0xffff0000, v210
	v_mul_f32_e32 v39, v39, v131
	v_lshlrev_b32_e32 v130, 16, v211
	v_mul_f32_e32 v40, v40, v130
	v_and_b32_e32 v131, 0xffff0000, v211
	v_mul_f32_e32 v41, v41, v131
	v_lshlrev_b32_e32 v130, 16, v212
	v_mul_f32_e32 v34, v34, v130
	v_and_b32_e32 v131, 0xffff0000, v212
	v_mul_f32_e32 v35, v35, v131
	v_lshlrev_b32_e32 v130, 16, v213
	v_mul_f32_e32 v36, v36, v130
	v_and_b32_e32 v131, 0xffff0000, v213
	v_mul_f32_e32 v37, v37, v131
	v_lshlrev_b32_e32 v130, 16, v214
	v_add_f32_e32 v38, v38, v130
	v_and_b32_e32 v131, 0xffff0000, v214
	v_add_f32_e32 v39, v39, v131
	v_lshlrev_b32_e32 v130, 16, v215
	v_add_f32_e32 v40, v40, v130
	v_and_b32_e32 v131, 0xffff0000, v215
	v_add_f32_e32 v41, v41, v131
	v_lshlrev_b32_e32 v130, 16, v216
	v_add_f32_e32 v34, v34, v130
	v_and_b32_e32 v131, 0xffff0000, v216
	v_add_f32_e32 v35, v35, v131
	v_lshlrev_b32_e32 v130, 16, v217
	v_add_f32_e32 v36, v36, v130
	v_and_b32_e32 v131, 0xffff0000, v217
	v_add_f32_e32 v37, v37, v131
	v_cvt_pk_bf16_f32 v38, v38, v39
	v_cvt_pk_bf16_f32 v39, v40, v41
	v_cvt_pk_bf16_f32 v40, v34, v35
	v_cvt_pk_bf16_f32 v41, v36, v37
	s_waitcnt vmcnt(6)
	v_lshlrev_b32_e32 v130, 16, v218
	v_mul_f32_e32 v30, v30, v130
	v_and_b32_e32 v131, 0xffff0000, v218
	v_mul_f32_e32 v31, v31, v131
	v_lshlrev_b32_e32 v130, 16, v219
	v_mul_f32_e32 v32, v32, v130
	v_and_b32_e32 v131, 0xffff0000, v219
	v_mul_f32_e32 v33, v33, v131
	v_lshlrev_b32_e32 v130, 16, v220
	v_mul_f32_e32 v26, v26, v130
	v_and_b32_e32 v131, 0xffff0000, v220
	v_mul_f32_e32 v27, v27, v131
	v_lshlrev_b32_e32 v130, 16, v221
	v_mul_f32_e32 v28, v28, v130
	v_and_b32_e32 v131, 0xffff0000, v221
	v_mul_f32_e32 v29, v29, v131
	v_lshlrev_b32_e32 v130, 16, v222
	v_add_f32_e32 v30, v30, v130
	v_and_b32_e32 v131, 0xffff0000, v222
	v_add_f32_e32 v31, v31, v131
	v_lshlrev_b32_e32 v130, 16, v223
	v_add_f32_e32 v32, v32, v130
	v_and_b32_e32 v131, 0xffff0000, v223
	v_add_f32_e32 v33, v33, v131
	v_lshlrev_b32_e32 v130, 16, v224
	v_add_f32_e32 v26, v26, v130
	v_and_b32_e32 v131, 0xffff0000, v224
	v_add_f32_e32 v27, v27, v131
	v_lshlrev_b32_e32 v130, 16, v225
	v_add_f32_e32 v28, v28, v130
	v_and_b32_e32 v131, 0xffff0000, v225
	v_add_f32_e32 v29, v29, v131
	v_cvt_pk_bf16_f32 v30, v30, v31
	v_cvt_pk_bf16_f32 v31, v32, v33
	v_cvt_pk_bf16_f32 v32, v26, v27
	v_cvt_pk_bf16_f32 v33, v28, v29
	s_waitcnt vmcnt(4)
	v_lshlrev_b32_e32 v130, 16, v226
	v_mul_f32_e32 v22, v22, v130
	v_and_b32_e32 v131, 0xffff0000, v226
	v_mul_f32_e32 v23, v23, v131
	v_lshlrev_b32_e32 v130, 16, v227
	v_mul_f32_e32 v24, v24, v130
	v_and_b32_e32 v131, 0xffff0000, v227
	v_mul_f32_e32 v25, v25, v131
	v_lshlrev_b32_e32 v130, 16, v228
	v_mul_f32_e32 v18, v18, v130
	v_and_b32_e32 v131, 0xffff0000, v228
	v_mul_f32_e32 v19, v19, v131
	v_lshlrev_b32_e32 v130, 16, v229
	v_mul_f32_e32 v20, v20, v130
	v_and_b32_e32 v131, 0xffff0000, v229
	v_mul_f32_e32 v21, v21, v131
	v_lshlrev_b32_e32 v130, 16, v230
	v_add_f32_e32 v22, v22, v130
	v_and_b32_e32 v131, 0xffff0000, v230
	v_add_f32_e32 v23, v23, v131
	v_lshlrev_b32_e32 v130, 16, v231
	v_add_f32_e32 v24, v24, v130
	v_and_b32_e32 v131, 0xffff0000, v231
	v_add_f32_e32 v25, v25, v131
	v_lshlrev_b32_e32 v130, 16, v232
	v_add_f32_e32 v18, v18, v130
	v_and_b32_e32 v131, 0xffff0000, v232
	v_add_f32_e32 v19, v19, v131
	v_lshlrev_b32_e32 v130, 16, v233
	v_add_f32_e32 v20, v20, v130
	v_and_b32_e32 v131, 0xffff0000, v233
	v_add_f32_e32 v21, v21, v131
	v_cvt_pk_bf16_f32 v22, v22, v23
	v_cvt_pk_bf16_f32 v23, v24, v25
	v_cvt_pk_bf16_f32 v24, v18, v19
	v_cvt_pk_bf16_f32 v25, v20, v21
	s_waitcnt vmcnt(2)
	v_lshlrev_b32_e32 v130, 16, v234
	v_mul_f32_e32 v14, v14, v130
	v_and_b32_e32 v131, 0xffff0000, v234
	v_mul_f32_e32 v15, v15, v131
	v_lshlrev_b32_e32 v130, 16, v235
	v_mul_f32_e32 v16, v16, v130
	v_and_b32_e32 v131, 0xffff0000, v235
	v_mul_f32_e32 v17, v17, v131
	v_lshlrev_b32_e32 v130, 16, v236
	v_mul_f32_e32 v10, v10, v130
	v_and_b32_e32 v131, 0xffff0000, v236
	v_mul_f32_e32 v11, v11, v131
	v_lshlrev_b32_e32 v130, 16, v237
	v_mul_f32_e32 v12, v12, v130
	v_and_b32_e32 v131, 0xffff0000, v237
	v_mul_f32_e32 v13, v13, v131
	v_lshlrev_b32_e32 v130, 16, v238
	v_add_f32_e32 v14, v14, v130
	v_and_b32_e32 v131, 0xffff0000, v238
	v_add_f32_e32 v15, v15, v131
	v_lshlrev_b32_e32 v130, 16, v239
	v_add_f32_e32 v16, v16, v130
	v_and_b32_e32 v131, 0xffff0000, v239
	v_add_f32_e32 v17, v17, v131
	v_lshlrev_b32_e32 v130, 16, v240
	v_add_f32_e32 v10, v10, v130
	v_and_b32_e32 v131, 0xffff0000, v240
	v_add_f32_e32 v11, v11, v131
	v_lshlrev_b32_e32 v130, 16, v241
	v_add_f32_e32 v12, v12, v130
	v_and_b32_e32 v131, 0xffff0000, v241
	v_add_f32_e32 v13, v13, v131
	v_cvt_pk_bf16_f32 v14, v14, v15
	v_cvt_pk_bf16_f32 v15, v16, v17
	v_cvt_pk_bf16_f32 v16, v10, v11
	v_cvt_pk_bf16_f32 v17, v12, v13
	s_waitcnt vmcnt(0)
	v_lshlrev_b32_e32 v130, 16, v242
	v_mul_f32_e32 v6, v6, v130
	v_and_b32_e32 v131, 0xffff0000, v242
	v_mul_f32_e32 v7, v7, v131
	v_lshlrev_b32_e32 v130, 16, v243
	v_mul_f32_e32 v8, v8, v130
	v_and_b32_e32 v131, 0xffff0000, v243
	v_mul_f32_e32 v9, v9, v131
	v_lshlrev_b32_e32 v130, 16, v244
	v_mul_f32_e32 v2, v2, v130
	v_and_b32_e32 v131, 0xffff0000, v244
	v_mul_f32_e32 v3, v3, v131
	v_lshlrev_b32_e32 v130, 16, v245
	v_mul_f32_e32 v4, v4, v130
	v_and_b32_e32 v131, 0xffff0000, v245
	v_mul_f32_e32 v5, v5, v131
	v_lshlrev_b32_e32 v130, 16, v246
	v_add_f32_e32 v6, v6, v130
	v_and_b32_e32 v131, 0xffff0000, v246
	v_add_f32_e32 v7, v7, v131
	v_lshlrev_b32_e32 v130, 16, v247
	v_add_f32_e32 v8, v8, v130
	v_and_b32_e32 v131, 0xffff0000, v247
	v_add_f32_e32 v9, v9, v131
	v_lshlrev_b32_e32 v130, 16, v248
	v_add_f32_e32 v2, v2, v130
	v_and_b32_e32 v131, 0xffff0000, v248
	v_add_f32_e32 v3, v3, v131
	v_lshlrev_b32_e32 v130, 16, v249
	v_add_f32_e32 v4, v4, v130
	v_and_b32_e32 v131, 0xffff0000, v249
	v_add_f32_e32 v5, v5, v131
	v_cvt_pk_bf16_f32 v6, v6, v7
	v_cvt_pk_bf16_f32 v7, v8, v9
	v_cvt_pk_bf16_f32 v8, v2, v3
	v_cvt_pk_bf16_f32 v9, v4, v5
	v_mov_b32_e32 v132, v160
	v_mov_b32_e32 v133, v161
	global_store_dwordx4 v[132:133], v[126:129], off
	global_store_dwordx4 v[132:133], v[118:121], off offset:256
	v_lshl_add_u64 v[132:133], v[132:133], 0, s[36:37]
	global_store_dwordx4 v[132:133], v[110:113], off
	global_store_dwordx4 v[132:133], v[102:105], off offset:256
	v_lshl_add_u64 v[132:133], v[132:133], 0, s[36:37]
	global_store_dwordx4 v[132:133], v[94:97], off
	global_store_dwordx4 v[132:133], v[86:89], off offset:256
	v_lshl_add_u64 v[132:133], v[132:133], 0, s[36:37]
	global_store_dwordx4 v[132:133], v[78:81], off
	global_store_dwordx4 v[132:133], v[70:73], off offset:256
	v_lshl_add_u64 v[132:133], v[132:133], 0, vcc
	global_store_dwordx4 v[132:133], v[62:65], off
	global_store_dwordx4 v[132:133], v[54:57], off offset:256
	v_lshl_add_u64 v[132:133], v[132:133], 0, s[36:37]
	global_store_dwordx4 v[132:133], v[46:49], off
	global_store_dwordx4 v[132:133], v[38:41], off offset:256
	v_lshl_add_u64 v[132:133], v[132:133], 0, s[36:37]
	global_store_dwordx4 v[132:133], v[30:33], off
	global_store_dwordx4 v[132:133], v[22:25], off offset:256
	v_lshl_add_u64 v[132:133], v[132:133], 0, s[36:37]
	global_store_dwordx4 v[132:133], v[14:17], off
	global_store_dwordx4 v[132:133], v[6:9], off offset:256
	s_branch .Lga_done
.Lga_first:
	global_load_dwordx4 v[186:189], v[156:157], off nt
	global_load_dwordx4 v[190:193], v[156:157], off offset:256 nt
	v_lshl_add_u64 v[156:157], v[156:157], 0, s[34:35]
	global_load_dwordx4 v[194:197], v[156:157], off nt
	global_load_dwordx4 v[198:201], v[156:157], off offset:256 nt
	v_lshl_add_u64 v[156:157], v[156:157], 0, s[34:35]
	global_load_dwordx4 v[218:221], v[156:157], off nt
	global_load_dwordx4 v[222:225], v[156:157], off offset:256 nt
	v_lshl_add_u64 v[156:157], v[156:157], 0, s[34:35]
	global_load_dwordx4 v[226:229], v[156:157], off nt
	global_load_dwordx4 v[230:233], v[156:157], off offset:256 nt
	v_lshl_add_u64 v[156:157], v[156:157], 0, s[8:9]
	s_waitcnt vmcnt(7)
	v_lshlrev_b32_e32 v130, 16, v186
	v_mul_f32_e32 v126, v126, v130
	v_and_b32_e32 v131, 0xffff0000, v186
	v_mul_f32_e32 v127, v127, v131
	v_lshlrev_b32_e32 v130, 16, v187
	v_mul_f32_e32 v128, v128, v130
	v_and_b32_e32 v131, 0xffff0000, v187
	v_mul_f32_e32 v129, v129, v131
	v_lshlrev_b32_e32 v130, 16, v188
	v_mul_f32_e32 v122, v122, v130
	v_and_b32_e32 v131, 0xffff0000, v188
	v_mul_f32_e32 v123, v123, v131
	v_lshlrev_b32_e32 v130, 16, v189
	v_mul_f32_e32 v124, v124, v130
	v_and_b32_e32 v131, 0xffff0000, v189
	v_mul_f32_e32 v125, v125, v131
	v_cvt_pk_bf16_f32 v126, v126, v127
	v_cvt_pk_bf16_f32 v127, v128, v129
	v_cvt_pk_bf16_f32 v128, v122, v123
	v_cvt_pk_bf16_f32 v129, v124, v125
	s_waitcnt vmcnt(6)
	v_lshlrev_b32_e32 v130, 16, v190
	v_mul_f32_e32 v118, v118, v130
	v_and_b32_e32 v131, 0xffff0000, v190
	v_mul_f32_e32 v119, v119, v131
	v_lshlrev_b32_e32 v130, 16, v191
	v_mul_f32_e32 v120, v120, v130
	v_and_b32_e32 v131, 0xffff0000, v191
	v_mul_f32_e32 v121, v121, v131
	v_lshlrev_b32_e32 v130, 16, v192
	v_mul_f32_e32 v114, v114, v130
	v_and_b32_e32 v131, 0xffff0000, v192
	v_mul_f32_e32 v115, v115, v131
	v_lshlrev_b32_e32 v130, 16, v193
	v_mul_f32_e32 v116, v116, v130
	v_and_b32_e32 v131, 0xffff0000, v193
	v_mul_f32_e32 v117, v117, v131
	v_cvt_pk_bf16_f32 v118, v118, v119
	v_cvt_pk_bf16_f32 v119, v120, v121
	v_cvt_pk_bf16_f32 v120, v114, v115
	v_cvt_pk_bf16_f32 v121, v116, v117
	s_waitcnt vmcnt(5)
	v_lshlrev_b32_e32 v130, 16, v194
	v_mul_f32_e32 v110, v110, v130
	v_and_b32_e32 v131, 0xffff0000, v194
	v_mul_f32_e32 v111, v111, v131
	v_lshlrev_b32_e32 v130, 16, v195
	v_mul_f32_e32 v112, v112, v130
	v_and_b32_e32 v131, 0xffff0000, v195
	v_mul_f32_e32 v113, v113, v131
	v_lshlrev_b32_e32 v130, 16, v196
	v_mul_f32_e32 v106, v106, v130
	v_and_b32_e32 v131, 0xffff0000, v196
	v_mul_f32_e32 v107, v107, v131
	v_lshlrev_b32_e32 v130, 16, v197
	v_mul_f32_e32 v108, v108, v130
	v_and_b32_e32 v131, 0xffff0000, v197
	v_mul_f32_e32 v109, v109, v131
	v_cvt_pk_bf16_f32 v110, v110, v111
	v_cvt_pk_bf16_f32 v111, v112, v113
	v_cvt_pk_bf16_f32 v112, v106, v107
	v_cvt_pk_bf16_f32 v113, v108, v109
	s_waitcnt vmcnt(4)
	v_lshlrev_b32_e32 v130, 16, v198
	v_mul_f32_e32 v102, v102, v130
	v_and_b32_e32 v131, 0xffff0000, v198
	v_mul_f32_e32 v103, v103, v131
	v_lshlrev_b32_e32 v130, 16, v199
	v_mul_f32_e32 v104, v104, v130
	v_and_b32_e32 v131, 0xffff0000, v199
	v_mul_f32_e32 v105, v105, v131
	v_lshlrev_b32_e32 v130, 16, v200
	v_mul_f32_e32 v98, v98, v130
	v_and_b32_e32 v131, 0xffff0000, v200
	v_mul_f32_e32 v99, v99, v131
	v_lshlrev_b32_e32 v130, 16, v201
	v_mul_f32_e32 v100, v100, v130
	v_and_b32_e32 v131, 0xffff0000, v201
	v_mul_f32_e32 v101, v101, v131
	v_cvt_pk_bf16_f32 v102, v102, v103
	v_cvt_pk_bf16_f32 v103, v104, v105
	v_cvt_pk_bf16_f32 v104, v98, v99
	v_cvt_pk_bf16_f32 v105, v100, v101
	global_load_dwordx4 v[186:189], v[156:157], off nt
	global_load_dwordx4 v[190:193], v[156:157], off offset:256 nt
	v_lshl_add_u64 v[156:157], v[156:157], 0, s[34:35]
	global_load_dwordx4 v[194:197], v[156:157], off nt
	global_load_dwordx4 v[198:201], v[156:157], off offset:256 nt
	v_lshl_add_u64 v[156:157], v[156:157], 0, s[34:35]
	s_waitcnt vmcnt(7)
	v_lshlrev_b32_e32 v130, 16, v218
	v_mul_f32_e32 v94, v94, v130
	v_and_b32_e32 v131, 0xffff0000, v218
	v_mul_f32_e32 v95, v95, v131
	v_lshlrev_b32_e32 v130, 16, v219
	v_mul_f32_e32 v96, v96, v130
	v_and_b32_e32 v131, 0xffff0000, v219
	v_mul_f32_e32 v97, v97, v131
	v_lshlrev_b32_e32 v130, 16, v220
	v_mul_f32_e32 v90, v90, v130
	v_and_b32_e32 v131, 0xffff0000, v220
	v_mul_f32_e32 v91, v91, v131
	v_lshlrev_b32_e32 v130, 16, v221
	v_mul_f32_e32 v92, v92, v130
	v_and_b32_e32 v131, 0xffff0000, v221
	v_mul_f32_e32 v93, v93, v131
	v_cvt_pk_bf16_f32 v94, v94, v95
	v_cvt_pk_bf16_f32 v95, v96, v97
	v_cvt_pk_bf16_f32 v96, v90, v91
	v_cvt_pk_bf16_f32 v97, v92, v93
	s_waitcnt vmcnt(6)
	v_lshlrev_b32_e32 v130, 16, v222
	v_mul_f32_e32 v86, v86, v130
	v_and_b32_e32 v131, 0xffff0000, v222
	v_mul_f32_e32 v87, v87, v131
	v_lshlrev_b32_e32 v130, 16, v223
	v_mul_f32_e32 v88, v88, v130
	v_and_b32_e32 v131, 0xffff0000, v223
	v_mul_f32_e32 v89, v89, v131
	v_lshlrev_b32_e32 v130, 16, v224
	v_mul_f32_e32 v82, v82, v130
	v_and_b32_e32 v131, 0xffff0000, v224
	v_mul_f32_e32 v83, v83, v131
	v_lshlrev_b32_e32 v130, 16, v225
	v_mul_f32_e32 v84, v84, v130
	v_and_b32_e32 v131, 0xffff0000, v225
	v_mul_f32_e32 v85, v85, v131
	v_cvt_pk_bf16_f32 v86, v86, v87
	v_cvt_pk_bf16_f32 v87, v88, v89
	v_cvt_pk_bf16_f32 v88, v82, v83
	v_cvt_pk_bf16_f32 v89, v84, v85
	s_waitcnt vmcnt(5)
	v_lshlrev_b32_e32 v130, 16, v226
	v_mul_f32_e32 v78, v78, v130
	v_and_b32_e32 v131, 0xffff0000, v226
	v_mul_f32_e32 v79, v79, v131
	v_lshlrev_b32_e32 v130, 16, v227
	v_mul_f32_e32 v80, v80, v130
	v_and_b32_e32 v131, 0xffff0000, v227
	v_mul_f32_e32 v81, v81, v131
	v_lshlrev_b32_e32 v130, 16, v228
	v_mul_f32_e32 v74, v74, v130
	v_and_b32_e32 v131, 0xffff0000, v228
	v_mul_f32_e32 v75, v75, v131
	v_lshlrev_b32_e32 v130, 16, v229
	v_mul_f32_e32 v76, v76, v130
	v_and_b32_e32 v131, 0xffff0000, v229
	v_mul_f32_e32 v77, v77, v131
	v_cvt_pk_bf16_f32 v78, v78, v79
	v_cvt_pk_bf16_f32 v79, v80, v81
	v_cvt_pk_bf16_f32 v80, v74, v75
	v_cvt_pk_bf16_f32 v81, v76, v77
	s_waitcnt vmcnt(4)
	v_lshlrev_b32_e32 v130, 16, v230
	v_mul_f32_e32 v70, v70, v130
	v_and_b32_e32 v131, 0xffff0000, v230
	v_mul_f32_e32 v71, v71, v131
	v_lshlrev_b32_e32 v130, 16, v231
	v_mul_f32_e32 v72, v72, v130
	v_and_b32_e32 v131, 0xffff0000, v231
	v_mul_f32_e32 v73, v73, v131
	v_lshlrev_b32_e32 v130, 16, v232
	v_mul_f32_e32 v66, v66, v130
	v_and_b32_e32 v131, 0xffff0000, v232
	v_mul_f32_e32 v67, v67, v131
	v_lshlrev_b32_e32 v130, 16, v233
	v_mul_f32_e32 v68, v68, v130
	v_and_b32_e32 v131, 0xffff0000, v233
	v_mul_f32_e32 v69, v69, v131
	v_cvt_pk_bf16_f32 v70, v70, v71
	v_cvt_pk_bf16_f32 v71, v72, v73
	v_cvt_pk_bf16_f32 v72, v66, v67
	v_cvt_pk_bf16_f32 v73, v68, v69
	global_load_dwordx4 v[218:221], v[156:157], off nt
	global_load_dwordx4 v[222:225], v[156:157], off offset:256 nt
	v_lshl_add_u64 v[156:157], v[156:157], 0, s[34:35]
	global_load_dwordx4 v[226:229], v[156:157], off nt
	global_load_dwordx4 v[230:233], v[156:157], off offset:256 nt
	s_waitcnt vmcnt(7)
	v_lshlrev_b32_e32 v130, 16, v186
	v_mul_f32_e32 v62, v62, v130
	v_and_b32_e32 v131, 0xffff0000, v186
	v_mul_f32_e32 v63, v63, v131
	v_lshlrev_b32_e32 v130, 16, v187
	v_mul_f32_e32 v64, v64, v130
	v_and_b32_e32 v131, 0xffff0000, v187
	v_mul_f32_e32 v65, v65, v131
	v_lshlrev_b32_e32 v130, 16, v188
	v_mul_f32_e32 v58, v58, v130
	v_and_b32_e32 v131, 0xffff0000, v188
	v_mul_f32_e32 v59, v59, v131
	v_lshlrev_b32_e32 v130, 16, v189
	v_mul_f32_e32 v60, v60, v130
	v_and_b32_e32 v131, 0xffff0000, v189
	v_mul_f32_e32 v61, v61, v131
	v_cvt_pk_bf16_f32 v62, v62, v63
	v_cvt_pk_bf16_f32 v63, v64, v65
	v_cvt_pk_bf16_f32 v64, v58, v59
	v_cvt_pk_bf16_f32 v65, v60, v61
	s_waitcnt vmcnt(6)
	v_lshlrev_b32_e32 v130, 16, v190
	v_mul_f32_e32 v54, v54, v130
	v_and_b32_e32 v131, 0xffff0000, v190
	v_mul_f32_e32 v55, v55, v131
	v_lshlrev_b32_e32 v130, 16, v191
	v_mul_f32_e32 v56, v56, v130
	v_and_b32_e32 v131, 0xffff0000, v191
	v_mul_f32_e32 v57, v57, v131
	v_lshlrev_b32_e32 v130, 16, v192
	v_mul_f32_e32 v50, v50, v130
	v_and_b32_e32 v131, 0xffff0000, v192
	v_mul_f32_e32 v51, v51, v131
	v_lshlrev_b32_e32 v130, 16, v193
	v_mul_f32_e32 v52, v52, v130
	v_and_b32_e32 v131, 0xffff0000, v193
	v_mul_f32_e32 v53, v53, v131
	v_cvt_pk_bf16_f32 v54, v54, v55
	v_cvt_pk_bf16_f32 v55, v56, v57
	v_cvt_pk_bf16_f32 v56, v50, v51
	v_cvt_pk_bf16_f32 v57, v52, v53
	s_waitcnt vmcnt(5)
	v_lshlrev_b32_e32 v130, 16, v194
	v_mul_f32_e32 v46, v46, v130
	v_and_b32_e32 v131, 0xffff0000, v194
	v_mul_f32_e32 v47, v47, v131
	v_lshlrev_b32_e32 v130, 16, v195
	v_mul_f32_e32 v48, v48, v130
	v_and_b32_e32 v131, 0xffff0000, v195
	v_mul_f32_e32 v49, v49, v131
	v_lshlrev_b32_e32 v130, 16, v196
	v_mul_f32_e32 v42, v42, v130
	v_and_b32_e32 v131, 0xffff0000, v196
	v_mul_f32_e32 v43, v43, v131
	v_lshlrev_b32_e32 v130, 16, v197
	v_mul_f32_e32 v44, v44, v130
	v_and_b32_e32 v131, 0xffff0000, v197
	v_mul_f32_e32 v45, v45, v131
	v_cvt_pk_bf16_f32 v46, v46, v47
	v_cvt_pk_bf16_f32 v47, v48, v49
	v_cvt_pk_bf16_f32 v48, v42, v43
	v_cvt_pk_bf16_f32 v49, v44, v45
	s_waitcnt vmcnt(4)
	v_lshlrev_b32_e32 v130, 16, v198
	v_mul_f32_e32 v38, v38, v130
	v_and_b32_e32 v131, 0xffff0000, v198
	v_mul_f32_e32 v39, v39, v131
	v_lshlrev_b32_e32 v130, 16, v199
	v_mul_f32_e32 v40, v40, v130
	v_and_b32_e32 v131, 0xffff0000, v199
	v_mul_f32_e32 v41, v41, v131
	v_lshlrev_b32_e32 v130, 16, v200
	v_mul_f32_e32 v34, v34, v130
	v_and_b32_e32 v131, 0xffff0000, v200
	v_mul_f32_e32 v35, v35, v131
	v_lshlrev_b32_e32 v130, 16, v201
	v_mul_f32_e32 v36, v36, v130
	v_and_b32_e32 v131, 0xffff0000, v201
	v_mul_f32_e32 v37, v37, v131
	v_cvt_pk_bf16_f32 v38, v38, v39
	v_cvt_pk_bf16_f32 v39, v40, v41
	v_cvt_pk_bf16_f32 v40, v34, v35
	v_cvt_pk_bf16_f32 v41, v36, v37
	s_waitcnt vmcnt(3)
	v_lshlrev_b32_e32 v130, 16, v218
	v_mul_f32_e32 v30, v30, v130
	v_and_b32_e32 v131, 0xffff0000, v218
	v_mul_f32_e32 v31, v31, v131
	v_lshlrev_b32_e32 v130, 16, v219
	v_mul_f32_e32 v32, v32, v130
	v_and_b32_e32 v131, 0xffff0000, v219
	v_mul_f32_e32 v33, v33, v131
	v_lshlrev_b32_e32 v130, 16, v220
	v_mul_f32_e32 v26, v26, v130
	v_and_b32_e32 v131, 0xffff0000, v220
	v_mul_f32_e32 v27, v27, v131
	v_lshlrev_b32_e32 v130, 16, v221
	v_mul_f32_e32 v28, v28, v130
	v_and_b32_e32 v131, 0xffff0000, v221
	v_mul_f32_e32 v29, v29, v131
	v_cvt_pk_bf16_f32 v30, v30, v31
	v_cvt_pk_bf16_f32 v31, v32, v33
	v_cvt_pk_bf16_f32 v32, v26, v27
	v_cvt_pk_bf16_f32 v33, v28, v29
	s_waitcnt vmcnt(2)
	v_lshlrev_b32_e32 v130, 16, v222
	v_mul_f32_e32 v22, v22, v130
	v_and_b32_e32 v131, 0xffff0000, v222
	v_mul_f32_e32 v23, v23, v131
	v_lshlrev_b32_e32 v130, 16, v223
	v_mul_f32_e32 v24, v24, v130
	v_and_b32_e32 v131, 0xffff0000, v223
	v_mul_f32_e32 v25, v25, v131
	v_lshlrev_b32_e32 v130, 16, v224
	v_mul_f32_e32 v18, v18, v130
	v_and_b32_e32 v131, 0xffff0000, v224
	v_mul_f32_e32 v19, v19, v131
	v_lshlrev_b32_e32 v130, 16, v225
	v_mul_f32_e32 v20, v20, v130
	v_and_b32_e32 v131, 0xffff0000, v225
	v_mul_f32_e32 v21, v21, v131
	v_cvt_pk_bf16_f32 v22, v22, v23
	v_cvt_pk_bf16_f32 v23, v24, v25
	v_cvt_pk_bf16_f32 v24, v18, v19
	v_cvt_pk_bf16_f32 v25, v20, v21
	s_waitcnt vmcnt(1)
	v_lshlrev_b32_e32 v130, 16, v226
	v_mul_f32_e32 v14, v14, v130
	v_and_b32_e32 v131, 0xffff0000, v226
	v_mul_f32_e32 v15, v15, v131
	v_lshlrev_b32_e32 v130, 16, v227
	v_mul_f32_e32 v16, v16, v130
	v_and_b32_e32 v131, 0xffff0000, v227
	v_mul_f32_e32 v17, v17, v131
	v_lshlrev_b32_e32 v130, 16, v228
	v_mul_f32_e32 v10, v10, v130
	v_and_b32_e32 v131, 0xffff0000, v228
	v_mul_f32_e32 v11, v11, v131
	v_lshlrev_b32_e32 v130, 16, v229
	v_mul_f32_e32 v12, v12, v130
	v_and_b32_e32 v131, 0xffff0000, v229
	v_mul_f32_e32 v13, v13, v131
	v_cvt_pk_bf16_f32 v14, v14, v15
	v_cvt_pk_bf16_f32 v15, v16, v17
	v_cvt_pk_bf16_f32 v16, v10, v11
	v_cvt_pk_bf16_f32 v17, v12, v13
	s_waitcnt vmcnt(0)
	v_lshlrev_b32_e32 v130, 16, v230
	v_mul_f32_e32 v6, v6, v130
	v_and_b32_e32 v131, 0xffff0000, v230
	v_mul_f32_e32 v7, v7, v131
	v_lshlrev_b32_e32 v130, 16, v231
	v_mul_f32_e32 v8, v8, v130
	v_and_b32_e32 v131, 0xffff0000, v231
	v_mul_f32_e32 v9, v9, v131
	v_lshlrev_b32_e32 v130, 16, v232
	v_mul_f32_e32 v2, v2, v130
	v_and_b32_e32 v131, 0xffff0000, v232
	v_mul_f32_e32 v3, v3, v131
	v_lshlrev_b32_e32 v130, 16, v233
	v_mul_f32_e32 v4, v4, v130
	v_and_b32_e32 v131, 0xffff0000, v233
	v_mul_f32_e32 v5, v5, v131
	v_cvt_pk_bf16_f32 v6, v6, v7
	v_cvt_pk_bf16_f32 v7, v8, v9
	v_cvt_pk_bf16_f32 v8, v2, v3
	v_cvt_pk_bf16_f32 v9, v4, v5
	v_mov_b32_e32 v132, v160
	v_mov_b32_e32 v133, v161
	global_store_dwordx4 v[132:133], v[126:129], off
	global_store_dwordx4 v[132:133], v[118:121], off offset:256
	v_lshl_add_u64 v[132:133], v[132:133], 0, s[36:37]
	global_store_dwordx4 v[132:133], v[110:113], off
	global_store_dwordx4 v[132:133], v[102:105], off offset:256
	v_lshl_add_u64 v[132:133], v[132:133], 0, s[36:37]
	global_store_dwordx4 v[132:133], v[94:97], off
	global_store_dwordx4 v[132:133], v[86:89], off offset:256
	v_lshl_add_u64 v[132:133], v[132:133], 0, s[36:37]
	global_store_dwordx4 v[132:133], v[78:81], off
	global_store_dwordx4 v[132:133], v[70:73], off offset:256
	v_lshl_add_u64 v[132:133], v[132:133], 0, vcc
	global_store_dwordx4 v[132:133], v[62:65], off
	global_store_dwordx4 v[132:133], v[54:57], off offset:256
	v_lshl_add_u64 v[132:133], v[132:133], 0, s[36:37]
	global_store_dwordx4 v[132:133], v[46:49], off
	global_store_dwordx4 v[132:133], v[38:41], off offset:256
	v_lshl_add_u64 v[132:133], v[132:133], 0, s[36:37]
	global_store_dwordx4 v[132:133], v[30:33], off
	global_store_dwordx4 v[132:133], v[22:25], off offset:256
	v_lshl_add_u64 v[132:133], v[132:133], 0, s[36:37]
	global_store_dwordx4 v[132:133], v[14:17], off
	global_store_dwordx4 v[132:133], v[6:9], off offset:256
